# leader write-back (buffer_wbl2) dropped at the barriers that follow write-through-only phases (P1, conv, P4, fix-up)
# speedup vs baseline: 1.0015x; 1.0015x over previous
; __device__ __forceinline__ unsigned xb_add(unsigned* p, unsigned v) { return __hip_atomic_fetch_add(p, v, __ATOMIC_RELAXED, __HIP_MEMORY_SCOPE_AGENT); }
; __device__ __forceinline__ void xcd_barrier(const XcdBarrier& b) {
;     ...
;         const unsigned old = xb_add(&bar[XB_XSUB(b.x)], 1u);
;         const unsigned gen = old / nloc;
;         if (old + 1u == (gen + 1u) * nloc) {
;             __builtin_amdgcn_fence(__ATOMIC_RELEASE, "agent");
;             asm volatile("s_waitcnt vmcnt(0)" ::: "memory");
;             const unsigned og = xb_add(&bar[XB_TOP], 1u);
;             const unsigned tg = og / nx;
;             if (og + 1u == (tg + 1u) * nx) xb_add(&bar[XB_TOPGEN], 1u);
.Lsk2_nl:
.LBB0_214:
	s_andn2_saveexec_b64 s[6:7], s[6:7]
	s_cbranch_execz .LBB0_232
	s_mov_b64 s[6:7], exec
	s_waitcnt lgkmcnt(0)
	s_waitcnt vmcnt(0)
	v_mbcnt_lo_u32_b32 v1, s6, 0
	v_mbcnt_hi_u32_b32 v1, s7, v1
	v_cmp_eq_u32_e32 vcc, 0, v1
	s_and_saveexec_b64 s[8:9], vcc
	s_cbranch_execz .LBB0_217
	s_bcnt1_i32_b64 s6, s[6:7]
	v_mov_b32_e32 v2, 0xffc3000
	v_mov_b32_e32 v3, s6
	global_atomic_add v2, v2, v3, s[88:89] offset:1024 sc0

; __device__ __forceinline__ unsigned xb_add(unsigned* p, unsigned v) { return __hip_atomic_fetch_add(p, v, __ATOMIC_RELAXED, __HIP_MEMORY_SCOPE_AGENT); }
; __device__ __forceinline__ void xcd_barrier(const XcdBarrier& b) {
;     ...
;         const unsigned old = xb_add(&bar[XB_XSUB(b.x)], 1u);
;         const unsigned gen = old / nloc;
;         if (old + 1u == (gen + 1u) * nloc) {
;             __builtin_amdgcn_fence(__ATOMIC_RELEASE, "agent");
;             asm volatile("s_waitcnt vmcnt(0)" ::: "memory");
;             const unsigned og = xb_add(&bar[XB_TOP], 1u);
;             const unsigned tg = og / nx;
;             if (og + 1u == (tg + 1u) * nx) xb_add(&bar[XB_TOPGEN], 1u);
.Lsk6_nl:
.LBB0_734:
	s_andn2_saveexec_b64 s[8:9], s[8:9]
	s_cbranch_execz .LBB0_752
	s_mov_b64 s[8:9], exec
	s_waitcnt lgkmcnt(0)
	s_waitcnt vmcnt(0)
	v_mbcnt_lo_u32_b32 v1, s8, 0
	v_mbcnt_hi_u32_b32 v1, s9, v1
	v_cmp_eq_u32_e32 vcc, 0, v1
	s_and_saveexec_b64 s[10:11], vcc
	s_cbranch_execz .LBB0_737
	s_bcnt1_i32_b64 s8, s[8:9]
	v_mov_b32_e32 v2, 0xffc3000
	v_mov_b32_e32 v3, s8
	global_atomic_add v2, v2, v3, s[88:89] offset:1024 sc0
